# k56: k52 + non-temporal (nt) stores in the in-projection GEMM epilogue (less dirty L2 data at the following grid barrier)
# speedup vs baseline: 1.0056x; 1.0056x over previous
; __host__ __device__ __forceinline__ size_t ux_off(int m, int ch) { return ((size_t)((ch >> 4) * UXROWS + (m >> 4)) * UXR + (m & 15)) * 16 + (ch & 15); }
; __device__ __forceinline__ unsigned pk2(float lo, float hi) { typedef __bf16 bf16x2_t_ __attribute__((ext_vector_type(2))); f32x2 v = {lo, hi}; return __builtin_bit_cast(unsigned, __builtin_convertvector(v, bf16x2_t_)); }
;     __device__ __forceinline__ void operator()(const f32x4 (&acc)[2][2][4][2], const pg8::Unit& u, int wr, int wc, int fr, int fq) const {
;     ...
;                 for (int bj = 0; bj < 2; ++bj) {
;                     u32x4 w; w.x = pk2(v[bj][0], v[bj][1]); w.y = pk2(v[bj][2], v[bj][3]); w.z = pk2(v[bj][4], v[bj][5]); w.w = pk2(v[bj][6], v[bj][7]);
;                     *(u32x4*)(bdst + (type == 0 ? ux_off(row, cb0 + bj * 32) : (size_t)(cb0 + bj * 32))) = w;
;                     if (fdst) { *(f32x4*)(fdst + cb0 + bj * 32) = (f32x4){v[bj][0], v[bj][1], v[bj][2], v[bj][3]}; *(f32x4*)(fdst + cb0 + bj * 32 + 4) = (f32x4){v[bj][4], v[bj][5], v[bj][6], v[bj][7]}; }
;                 }
.LBB0_306:
	v_lshlrev_b32_e32 v190, 2, v152
	v_mov_b32_e32 v191, v153
	v_cmp_ne_u64_e64 s[10:11], 0, v[116:117]
	v_lshl_add_u64 v[114:115], v[116:117], 0, v[190:191]
	v_cvt_pk_bf16_f32 v120, v128, v129
	v_cvt_pk_bf16_f32 v121, v130, v131
	v_cvt_pk_bf16_f32 v122, v132, v133
	v_cvt_pk_bf16_f32 v123, v134, v135
	v_lshl_add_u64 v[116:117], v[118:119], 1, v[112:113]
	global_store_dwordx4 v[116:117], v[120:123], off nt
	s_and_saveexec_b64 s[8:9], s[10:11]
	s_cbranch_execz .LBB0_308
	global_store_dwordx4 v[114:115], v[128:131], off nt
	global_store_dwordx4 v[114:115], v[132:135], off offset:16 nt

; __host__ __device__ __forceinline__ size_t ux_off(int m, int ch) { return ((size_t)((ch >> 4) * UXROWS + (m >> 4)) * UXR + (m & 15)) * 16 + (ch & 15); }
; __device__ __forceinline__ unsigned pk2(float lo, float hi) { typedef __bf16 bf16x2_t_ __attribute__((ext_vector_type(2))); f32x2 v = {lo, hi}; return __builtin_bit_cast(unsigned, __builtin_convertvector(v, bf16x2_t_)); }
;     __device__ __forceinline__ void operator()(const f32x4 (&acc)[2][2][4][2], const pg8::Unit& u, int wr, int wc, int fr, int fq) const {
;     ...
;                 for (int bj = 0; bj < 2; ++bj) {
;                     u32x4 w; w.x = pk2(v[bj][0], v[bj][1]); w.y = pk2(v[bj][2], v[bj][3]); w.z = pk2(v[bj][4], v[bj][5]); w.w = pk2(v[bj][6], v[bj][7]);
;                     *(u32x4*)(bdst + (type == 0 ? ux_off(row, cb0 + bj * 32) : (size_t)(cb0 + bj * 32))) = w;
;                     if (fdst) { *(f32x4*)(fdst + cb0 + bj * 32) = (f32x4){v[bj][0], v[bj][1], v[bj][2], v[bj][3]}; *(f32x4*)(fdst + cb0 + bj * 32 + 4) = (f32x4){v[bj][4], v[bj][5], v[bj][6], v[bj][7]}; }
;                 }
.LBB0_312:
	v_cvt_pk_bf16_f32 v118, v136, v137
	v_cvt_pk_bf16_f32 v119, v138, v139
	v_cvt_pk_bf16_f32 v120, v140, v141
	v_cvt_pk_bf16_f32 v121, v142, v143
	v_lshl_add_u64 v[112:113], v[116:117], 1, v[112:113]
	global_store_dwordx4 v[112:113], v[118:121], off nt
	s_and_saveexec_b64 s[12:13], s[10:11]
	s_cbranch_execz .LBB0_314
	global_store_dwordx4 v[114:115], v[136:139], off offset:128 nt
	global_store_dwordx4 v[114:115], v[140:143], off offset:144 nt

; __host__ __device__ __forceinline__ size_t ux_off(int m, int ch) { return ((size_t)((ch >> 4) * UXROWS + (m >> 4)) * UXR + (m & 15)) * 16 + (ch & 15); }
; __device__ __forceinline__ unsigned pk2(float lo, float hi) { typedef __bf16 bf16x2_t_ __attribute__((ext_vector_type(2))); f32x2 v = {lo, hi}; return __builtin_bit_cast(unsigned, __builtin_convertvector(v, bf16x2_t_)); }
;     __device__ __forceinline__ void operator()(const f32x4 (&acc)[2][2][4][2], const pg8::Unit& u, int wr, int wc, int fr, int fq) const {
;     ...
;                 for (int bj = 0; bj < 2; ++bj) {
;                     u32x4 w; w.x = pk2(v[bj][0], v[bj][1]); w.y = pk2(v[bj][2], v[bj][3]); w.z = pk2(v[bj][4], v[bj][5]); w.w = pk2(v[bj][6], v[bj][7]);
;                     *(u32x4*)(bdst + (type == 0 ? ux_off(row, cb0 + bj * 32) : (size_t)(cb0 + bj * 32))) = w;
;                     if (fdst) { *(f32x4*)(fdst + cb0 + bj * 32) = (f32x4){v[bj][0], v[bj][1], v[bj][2], v[bj][3]}; *(f32x4*)(fdst + cb0 + bj * 32 + 4) = (f32x4){v[bj][4], v[bj][5], v[bj][6], v[bj][7]}; }
;                 }
.LBB0_339:
	v_mov_b32_e32 v191, v153
	v_cmp_ne_u64_e64 s[14:15], 0, v[100:101]
	v_lshl_add_u64 v[98:99], v[100:101], 0, v[190:191]
	v_cvt_pk_bf16_f32 v104, v112, v113
	v_cvt_pk_bf16_f32 v105, v114, v115
	v_cvt_pk_bf16_f32 v106, v116, v117
	v_cvt_pk_bf16_f32 v107, v118, v119
	v_lshl_add_u64 v[100:101], v[102:103], 1, v[96:97]
	global_store_dwordx4 v[100:101], v[104:107], off nt
	s_and_saveexec_b64 s[84:85], s[14:15]
	s_cbranch_execz .LBB0_341
	global_store_dwordx4 v[98:99], v[112:115], off nt
	global_store_dwordx4 v[98:99], v[116:119], off offset:16 nt

; __host__ __device__ __forceinline__ size_t ux_off(int m, int ch) { return ((size_t)((ch >> 4) * UXROWS + (m >> 4)) * UXR + (m & 15)) * 16 + (ch & 15); }
; __device__ __forceinline__ unsigned pk2(float lo, float hi) { typedef __bf16 bf16x2_t_ __attribute__((ext_vector_type(2))); f32x2 v = {lo, hi}; return __builtin_bit_cast(unsigned, __builtin_convertvector(v, bf16x2_t_)); }
;     __device__ __forceinline__ void operator()(const f32x4 (&acc)[2][2][4][2], const pg8::Unit& u, int wr, int wc, int fr, int fq) const {
;     ...
;                 for (int bj = 0; bj < 2; ++bj) {
;                     u32x4 w; w.x = pk2(v[bj][0], v[bj][1]); w.y = pk2(v[bj][2], v[bj][3]); w.z = pk2(v[bj][4], v[bj][5]); w.w = pk2(v[bj][6], v[bj][7]);
;                     *(u32x4*)(bdst + (type == 0 ? ux_off(row, cb0 + bj * 32) : (size_t)(cb0 + bj * 32))) = w;
;                     if (fdst) { *(f32x4*)(fdst + cb0 + bj * 32) = (f32x4){v[bj][0], v[bj][1], v[bj][2], v[bj][3]}; *(f32x4*)(fdst + cb0 + bj * 32 + 4) = (f32x4){v[bj][4], v[bj][5], v[bj][6], v[bj][7]}; }
;                 }
.LBB0_345:
	v_cvt_pk_bf16_f32 v102, v120, v121
	v_cvt_pk_bf16_f32 v103, v122, v123
	v_cvt_pk_bf16_f32 v104, v124, v125
	v_cvt_pk_bf16_f32 v105, v126, v127
	v_lshl_add_u64 v[96:97], v[100:101], 1, v[96:97]
	global_store_dwordx4 v[96:97], v[102:105], off nt
	s_and_saveexec_b64 s[84:85], s[14:15]
	s_cbranch_execz .LBB0_347
	global_store_dwordx4 v[98:99], v[120:123], off offset:128 nt
	global_store_dwordx4 v[98:99], v[124:127], off offset:144 nt

; __host__ __device__ __forceinline__ size_t ux_off(int m, int ch) { return ((size_t)((ch >> 4) * UXROWS + (m >> 4)) * UXR + (m & 15)) * 16 + (ch & 15); }
; __device__ __forceinline__ unsigned pk2(float lo, float hi) { typedef __bf16 bf16x2_t_ __attribute__((ext_vector_type(2))); f32x2 v = {lo, hi}; return __builtin_bit_cast(unsigned, __builtin_convertvector(v, bf16x2_t_)); }
;     __device__ __forceinline__ void operator()(const f32x4 (&acc)[2][2][4][2], const pg8::Unit& u, int wr, int wc, int fr, int fq) const {
;     ...
;                 for (int bj = 0; bj < 2; ++bj) {
;                     u32x4 w; w.x = pk2(v[bj][0], v[bj][1]); w.y = pk2(v[bj][2], v[bj][3]); w.z = pk2(v[bj][4], v[bj][5]); w.w = pk2(v[bj][6], v[bj][7]);
;                     *(u32x4*)(bdst + (type == 0 ? ux_off(row, cb0 + bj * 32) : (size_t)(cb0 + bj * 32))) = w;
;                     if (fdst) { *(f32x4*)(fdst + cb0 + bj * 32) = (f32x4){v[bj][0], v[bj][1], v[bj][2], v[bj][3]}; *(f32x4*)(fdst + cb0 + bj * 32 + 4) = (f32x4){v[bj][4], v[bj][5], v[bj][6], v[bj][7]}; }
;                 }
.LBB0_372:
	v_mov_b32_e32 v191, v153
	v_cmp_ne_u64_e64 s[14:15], 0, v[84:85]
	v_lshl_add_u64 v[82:83], v[84:85], 0, v[190:191]
	v_cvt_pk_bf16_f32 v88, v96, v97
	v_cvt_pk_bf16_f32 v89, v98, v99
	v_cvt_pk_bf16_f32 v90, v100, v101
	v_cvt_pk_bf16_f32 v91, v102, v103
	v_lshl_add_u64 v[84:85], v[86:87], 1, v[80:81]
	global_store_dwordx4 v[84:85], v[88:91], off nt
	s_and_saveexec_b64 s[84:85], s[14:15]
	s_cbranch_execz .LBB0_374
	global_store_dwordx4 v[82:83], v[96:99], off nt
	global_store_dwordx4 v[82:83], v[100:103], off offset:16 nt

; __host__ __device__ __forceinline__ size_t ux_off(int m, int ch) { return ((size_t)((ch >> 4) * UXROWS + (m >> 4)) * UXR + (m & 15)) * 16 + (ch & 15); }
; __device__ __forceinline__ unsigned pk2(float lo, float hi) { typedef __bf16 bf16x2_t_ __attribute__((ext_vector_type(2))); f32x2 v = {lo, hi}; return __builtin_bit_cast(unsigned, __builtin_convertvector(v, bf16x2_t_)); }
;     __device__ __forceinline__ void operator()(const f32x4 (&acc)[2][2][4][2], const pg8::Unit& u, int wr, int wc, int fr, int fq) const {
;     ...
;                 for (int bj = 0; bj < 2; ++bj) {
;                     u32x4 w; w.x = pk2(v[bj][0], v[bj][1]); w.y = pk2(v[bj][2], v[bj][3]); w.z = pk2(v[bj][4], v[bj][5]); w.w = pk2(v[bj][6], v[bj][7]);
;                     *(u32x4*)(bdst + (type == 0 ? ux_off(row, cb0 + bj * 32) : (size_t)(cb0 + bj * 32))) = w;
;                     if (fdst) { *(f32x4*)(fdst + cb0 + bj * 32) = (f32x4){v[bj][0], v[bj][1], v[bj][2], v[bj][3]}; *(f32x4*)(fdst + cb0 + bj * 32 + 4) = (f32x4){v[bj][4], v[bj][5], v[bj][6], v[bj][7]}; }
;                 }
.LBB0_378:
	v_cvt_pk_bf16_f32 v86, v104, v105
	v_cvt_pk_bf16_f32 v87, v106, v107
	v_cvt_pk_bf16_f32 v88, v108, v109
	v_cvt_pk_bf16_f32 v89, v110, v111
	v_lshl_add_u64 v[80:81], v[84:85], 1, v[80:81]
	global_store_dwordx4 v[80:81], v[86:89], off nt
	s_and_saveexec_b64 s[84:85], s[14:15]
	s_cbranch_execz .LBB0_380
	global_store_dwordx4 v[82:83], v[104:107], off offset:128 nt
	global_store_dwordx4 v[82:83], v[108:111], off offset:144 nt

; __host__ __device__ __forceinline__ size_t ux_off(int m, int ch) { return ((size_t)((ch >> 4) * UXROWS + (m >> 4)) * UXR + (m & 15)) * 16 + (ch & 15); }
; __device__ __forceinline__ unsigned pk2(float lo, float hi) { typedef __bf16 bf16x2_t_ __attribute__((ext_vector_type(2))); f32x2 v = {lo, hi}; return __builtin_bit_cast(unsigned, __builtin_convertvector(v, bf16x2_t_)); }
;     __device__ __forceinline__ void operator()(const f32x4 (&acc)[2][2][4][2], const pg8::Unit& u, int wr, int wc, int fr, int fq) const {
;     ...
;                 for (int bj = 0; bj < 2; ++bj) {
;                     u32x4 w; w.x = pk2(v[bj][0], v[bj][1]); w.y = pk2(v[bj][2], v[bj][3]); w.z = pk2(v[bj][4], v[bj][5]); w.w = pk2(v[bj][6], v[bj][7]);
;                     *(u32x4*)(bdst + (type == 0 ? ux_off(row, cb0 + bj * 32) : (size_t)(cb0 + bj * 32))) = w;
;                     if (fdst) { *(f32x4*)(fdst + cb0 + bj * 32) = (f32x4){v[bj][0], v[bj][1], v[bj][2], v[bj][3]}; *(f32x4*)(fdst + cb0 + bj * 32 + 4) = (f32x4){v[bj][4], v[bj][5], v[bj][6], v[bj][7]}; }
;                 }
.LBB0_405:
	v_mov_b32_e32 v191, v153
	v_cmp_ne_u64_e64 s[14:15], 0, v[68:69]
	v_lshl_add_u64 v[66:67], v[68:69], 0, v[190:191]
	v_cvt_pk_bf16_f32 v72, v80, v81
	v_cvt_pk_bf16_f32 v73, v82, v83
	v_cvt_pk_bf16_f32 v74, v84, v85
	v_cvt_pk_bf16_f32 v75, v86, v87
	v_lshl_add_u64 v[68:69], v[70:71], 1, v[64:65]
	global_store_dwordx4 v[68:69], v[72:75], off nt
	s_and_saveexec_b64 s[84:85], s[14:15]
	s_cbranch_execz .LBB0_407
	global_store_dwordx4 v[66:67], v[80:83], off nt
	global_store_dwordx4 v[66:67], v[84:87], off offset:16 nt

; __host__ __device__ __forceinline__ size_t ux_off(int m, int ch) { return ((size_t)((ch >> 4) * UXROWS + (m >> 4)) * UXR + (m & 15)) * 16 + (ch & 15); }
; __device__ __forceinline__ unsigned pk2(float lo, float hi) { typedef __bf16 bf16x2_t_ __attribute__((ext_vector_type(2))); f32x2 v = {lo, hi}; return __builtin_bit_cast(unsigned, __builtin_convertvector(v, bf16x2_t_)); }
;     __device__ __forceinline__ void operator()(const f32x4 (&acc)[2][2][4][2], const pg8::Unit& u, int wr, int wc, int fr, int fq) const {
;     ...
;                 for (int bj = 0; bj < 2; ++bj) {
;                     u32x4 w; w.x = pk2(v[bj][0], v[bj][1]); w.y = pk2(v[bj][2], v[bj][3]); w.z = pk2(v[bj][4], v[bj][5]); w.w = pk2(v[bj][6], v[bj][7]);
;                     *(u32x4*)(bdst + (type == 0 ? ux_off(row, cb0 + bj * 32) : (size_t)(cb0 + bj * 32))) = w;
;                     if (fdst) { *(f32x4*)(fdst + cb0 + bj * 32) = (f32x4){v[bj][0], v[bj][1], v[bj][2], v[bj][3]}; *(f32x4*)(fdst + cb0 + bj * 32 + 4) = (f32x4){v[bj][4], v[bj][5], v[bj][6], v[bj][7]}; }
;                 }
.LBB0_411:
	v_cvt_pk_bf16_f32 v70, v88, v89
	v_cvt_pk_bf16_f32 v71, v90, v91
	v_cvt_pk_bf16_f32 v72, v92, v93
	v_cvt_pk_bf16_f32 v73, v94, v95
	v_lshl_add_u64 v[64:65], v[68:69], 1, v[64:65]
	global_store_dwordx4 v[64:65], v[70:73], off nt
	s_and_saveexec_b64 s[84:85], s[14:15]
	s_cbranch_execz .LBB0_413
	global_store_dwordx4 v[66:67], v[88:91], off offset:128 nt
	global_store_dwordx4 v[66:67], v[92:95], off offset:144 nt

; __host__ __device__ __forceinline__ size_t ux_off(int m, int ch) { return ((size_t)((ch >> 4) * UXROWS + (m >> 4)) * UXR + (m & 15)) * 16 + (ch & 15); }
; __device__ __forceinline__ unsigned pk2(float lo, float hi) { typedef __bf16 bf16x2_t_ __attribute__((ext_vector_type(2))); f32x2 v = {lo, hi}; return __builtin_bit_cast(unsigned, __builtin_convertvector(v, bf16x2_t_)); }
;     __device__ __forceinline__ void operator()(const f32x4 (&acc)[2][2][4][2], const pg8::Unit& u, int wr, int wc, int fr, int fq) const {
;     ...
;                 for (int bj = 0; bj < 2; ++bj) {
;                     u32x4 w; w.x = pk2(v[bj][0], v[bj][1]); w.y = pk2(v[bj][2], v[bj][3]); w.z = pk2(v[bj][4], v[bj][5]); w.w = pk2(v[bj][6], v[bj][7]);
;                     *(u32x4*)(bdst + (type == 0 ? ux_off(row, cb0 + bj * 32) : (size_t)(cb0 + bj * 32))) = w;
;                     if (fdst) { *(f32x4*)(fdst + cb0 + bj * 32) = (f32x4){v[bj][0], v[bj][1], v[bj][2], v[bj][3]}; *(f32x4*)(fdst + cb0 + bj * 32 + 4) = (f32x4){v[bj][4], v[bj][5], v[bj][6], v[bj][7]}; }
;                 }
.LBB0_438:
	v_mov_b32_e32 v191, v153
	v_cmp_ne_u64_e64 s[14:15], 0, v[52:53]
	v_lshl_add_u64 v[50:51], v[52:53], 0, v[190:191]
	v_cvt_pk_bf16_f32 v56, v64, v65
	v_cvt_pk_bf16_f32 v57, v66, v67
	v_cvt_pk_bf16_f32 v58, v68, v69
	v_cvt_pk_bf16_f32 v59, v70, v71
	v_lshl_add_u64 v[52:53], v[54:55], 1, v[48:49]
	global_store_dwordx4 v[52:53], v[56:59], off nt
	s_and_saveexec_b64 s[84:85], s[14:15]
	s_cbranch_execz .LBB0_440
	global_store_dwordx4 v[50:51], v[64:67], off nt
	global_store_dwordx4 v[50:51], v[68:71], off offset:16 nt

; __host__ __device__ __forceinline__ size_t ux_off(int m, int ch) { return ((size_t)((ch >> 4) * UXROWS + (m >> 4)) * UXR + (m & 15)) * 16 + (ch & 15); }
; __device__ __forceinline__ unsigned pk2(float lo, float hi) { typedef __bf16 bf16x2_t_ __attribute__((ext_vector_type(2))); f32x2 v = {lo, hi}; return __builtin_bit_cast(unsigned, __builtin_convertvector(v, bf16x2_t_)); }
;     __device__ __forceinline__ void operator()(const f32x4 (&acc)[2][2][4][2], const pg8::Unit& u, int wr, int wc, int fr, int fq) const {
;     ...
;                 for (int bj = 0; bj < 2; ++bj) {
;                     u32x4 w; w.x = pk2(v[bj][0], v[bj][1]); w.y = pk2(v[bj][2], v[bj][3]); w.z = pk2(v[bj][4], v[bj][5]); w.w = pk2(v[bj][6], v[bj][7]);
;                     *(u32x4*)(bdst + (type == 0 ? ux_off(row, cb0 + bj * 32) : (size_t)(cb0 + bj * 32))) = w;
;                     if (fdst) { *(f32x4*)(fdst + cb0 + bj * 32) = (f32x4){v[bj][0], v[bj][1], v[bj][2], v[bj][3]}; *(f32x4*)(fdst + cb0 + bj * 32 + 4) = (f32x4){v[bj][4], v[bj][5], v[bj][6], v[bj][7]}; }
;                 }
.LBB0_444:
	v_cvt_pk_bf16_f32 v54, v72, v73
	v_cvt_pk_bf16_f32 v55, v74, v75
	v_cvt_pk_bf16_f32 v56, v76, v77
	v_cvt_pk_bf16_f32 v57, v78, v79
	v_lshl_add_u64 v[48:49], v[52:53], 1, v[48:49]
	global_store_dwordx4 v[48:49], v[54:57], off nt
	s_and_saveexec_b64 s[84:85], s[14:15]
	s_cbranch_execz .LBB0_446
	global_store_dwordx4 v[50:51], v[72:75], off offset:128 nt
	global_store_dwordx4 v[50:51], v[76:79], off offset:144 nt

; __host__ __device__ __forceinline__ size_t ux_off(int m, int ch) { return ((size_t)((ch >> 4) * UXROWS + (m >> 4)) * UXR + (m & 15)) * 16 + (ch & 15); }
; __device__ __forceinline__ unsigned pk2(float lo, float hi) { typedef __bf16 bf16x2_t_ __attribute__((ext_vector_type(2))); f32x2 v = {lo, hi}; return __builtin_bit_cast(unsigned, __builtin_convertvector(v, bf16x2_t_)); }
;     __device__ __forceinline__ void operator()(const f32x4 (&acc)[2][2][4][2], const pg8::Unit& u, int wr, int wc, int fr, int fq) const {
;     ...
;                 for (int bj = 0; bj < 2; ++bj) {
;                     u32x4 w; w.x = pk2(v[bj][0], v[bj][1]); w.y = pk2(v[bj][2], v[bj][3]); w.z = pk2(v[bj][4], v[bj][5]); w.w = pk2(v[bj][6], v[bj][7]);
;                     *(u32x4*)(bdst + (type == 0 ? ux_off(row, cb0 + bj * 32) : (size_t)(cb0 + bj * 32))) = w;
;                     if (fdst) { *(f32x4*)(fdst + cb0 + bj * 32) = (f32x4){v[bj][0], v[bj][1], v[bj][2], v[bj][3]}; *(f32x4*)(fdst + cb0 + bj * 32 + 4) = (f32x4){v[bj][4], v[bj][5], v[bj][6], v[bj][7]}; }
;                 }
.LBB0_471:
	v_mov_b32_e32 v191, v153
	v_cmp_ne_u64_e64 s[14:15], 0, v[36:37]
	v_lshl_add_u64 v[34:35], v[36:37], 0, v[190:191]
	v_cvt_pk_bf16_f32 v40, v48, v49
	v_cvt_pk_bf16_f32 v41, v50, v51
	v_cvt_pk_bf16_f32 v42, v52, v53
	v_cvt_pk_bf16_f32 v43, v54, v55
	v_lshl_add_u64 v[36:37], v[38:39], 1, v[32:33]
	global_store_dwordx4 v[36:37], v[40:43], off nt
	s_and_saveexec_b64 s[84:85], s[14:15]
	s_cbranch_execz .LBB0_473
	global_store_dwordx4 v[34:35], v[48:51], off nt
	global_store_dwordx4 v[34:35], v[52:55], off offset:16 nt

; __host__ __device__ __forceinline__ size_t ux_off(int m, int ch) { return ((size_t)((ch >> 4) * UXROWS + (m >> 4)) * UXR + (m & 15)) * 16 + (ch & 15); }
; __device__ __forceinline__ unsigned pk2(float lo, float hi) { typedef __bf16 bf16x2_t_ __attribute__((ext_vector_type(2))); f32x2 v = {lo, hi}; return __builtin_bit_cast(unsigned, __builtin_convertvector(v, bf16x2_t_)); }
;     __device__ __forceinline__ void operator()(const f32x4 (&acc)[2][2][4][2], const pg8::Unit& u, int wr, int wc, int fr, int fq) const {
;     ...
;                 for (int bj = 0; bj < 2; ++bj) {
;                     u32x4 w; w.x = pk2(v[bj][0], v[bj][1]); w.y = pk2(v[bj][2], v[bj][3]); w.z = pk2(v[bj][4], v[bj][5]); w.w = pk2(v[bj][6], v[bj][7]);
;                     *(u32x4*)(bdst + (type == 0 ? ux_off(row, cb0 + bj * 32) : (size_t)(cb0 + bj * 32))) = w;
;                     if (fdst) { *(f32x4*)(fdst + cb0 + bj * 32) = (f32x4){v[bj][0], v[bj][1], v[bj][2], v[bj][3]}; *(f32x4*)(fdst + cb0 + bj * 32 + 4) = (f32x4){v[bj][4], v[bj][5], v[bj][6], v[bj][7]}; }
;                 }
.LBB0_477:
	v_cvt_pk_bf16_f32 v38, v56, v57
	v_cvt_pk_bf16_f32 v39, v58, v59
	v_cvt_pk_bf16_f32 v40, v60, v61
	v_cvt_pk_bf16_f32 v41, v62, v63
	v_lshl_add_u64 v[32:33], v[36:37], 1, v[32:33]
	global_store_dwordx4 v[32:33], v[38:41], off nt
	s_and_saveexec_b64 s[84:85], s[14:15]
	s_cbranch_execz .LBB0_479
	global_store_dwordx4 v[34:35], v[56:59], off offset:128 nt
	global_store_dwordx4 v[34:35], v[60:63], off offset:144 nt

; __host__ __device__ __forceinline__ size_t ux_off(int m, int ch) { return ((size_t)((ch >> 4) * UXROWS + (m >> 4)) * UXR + (m & 15)) * 16 + (ch & 15); }
; __device__ __forceinline__ unsigned pk2(float lo, float hi) { typedef __bf16 bf16x2_t_ __attribute__((ext_vector_type(2))); f32x2 v = {lo, hi}; return __builtin_bit_cast(unsigned, __builtin_convertvector(v, bf16x2_t_)); }
;     __device__ __forceinline__ void operator()(const f32x4 (&acc)[2][2][4][2], const pg8::Unit& u, int wr, int wc, int fr, int fq) const {
;     ...
;                 for (int bj = 0; bj < 2; ++bj) {
;                     u32x4 w; w.x = pk2(v[bj][0], v[bj][1]); w.y = pk2(v[bj][2], v[bj][3]); w.z = pk2(v[bj][4], v[bj][5]); w.w = pk2(v[bj][6], v[bj][7]);
;                     *(u32x4*)(bdst + (type == 0 ? ux_off(row, cb0 + bj * 32) : (size_t)(cb0 + bj * 32))) = w;
;                     if (fdst) { *(f32x4*)(fdst + cb0 + bj * 32) = (f32x4){v[bj][0], v[bj][1], v[bj][2], v[bj][3]}; *(f32x4*)(fdst + cb0 + bj * 32 + 4) = (f32x4){v[bj][4], v[bj][5], v[bj][6], v[bj][7]}; }
;                 }
.LBB0_504:
	v_mov_b32_e32 v191, v153
	v_cmp_ne_u64_e64 s[14:15], 0, v[20:21]
	v_lshl_add_u64 v[18:19], v[20:21], 0, v[190:191]
	v_cvt_pk_bf16_f32 v24, v32, v33
	v_cvt_pk_bf16_f32 v25, v34, v35
	v_cvt_pk_bf16_f32 v26, v36, v37
	v_cvt_pk_bf16_f32 v27, v38, v39
	v_lshl_add_u64 v[20:21], v[22:23], 1, v[16:17]
	global_store_dwordx4 v[20:21], v[24:27], off nt
	s_and_saveexec_b64 s[84:85], s[14:15]
	s_cbranch_execz .LBB0_506
	global_store_dwordx4 v[18:19], v[32:35], off nt
	global_store_dwordx4 v[18:19], v[36:39], off offset:16 nt

; __host__ __device__ __forceinline__ size_t ux_off(int m, int ch) { return ((size_t)((ch >> 4) * UXROWS + (m >> 4)) * UXR + (m & 15)) * 16 + (ch & 15); }
; __device__ __forceinline__ unsigned pk2(float lo, float hi) { typedef __bf16 bf16x2_t_ __attribute__((ext_vector_type(2))); f32x2 v = {lo, hi}; return __builtin_bit_cast(unsigned, __builtin_convertvector(v, bf16x2_t_)); }
;     __device__ __forceinline__ void operator()(const f32x4 (&acc)[2][2][4][2], const pg8::Unit& u, int wr, int wc, int fr, int fq) const {
;     ...
;                 for (int bj = 0; bj < 2; ++bj) {
;                     u32x4 w; w.x = pk2(v[bj][0], v[bj][1]); w.y = pk2(v[bj][2], v[bj][3]); w.z = pk2(v[bj][4], v[bj][5]); w.w = pk2(v[bj][6], v[bj][7]);
;                     *(u32x4*)(bdst + (type == 0 ? ux_off(row, cb0 + bj * 32) : (size_t)(cb0 + bj * 32))) = w;
;                     if (fdst) { *(f32x4*)(fdst + cb0 + bj * 32) = (f32x4){v[bj][0], v[bj][1], v[bj][2], v[bj][3]}; *(f32x4*)(fdst + cb0 + bj * 32 + 4) = (f32x4){v[bj][4], v[bj][5], v[bj][6], v[bj][7]}; }
;                 }
.LBB0_510:
	v_cvt_pk_bf16_f32 v22, v40, v41
	v_cvt_pk_bf16_f32 v23, v42, v43
	v_cvt_pk_bf16_f32 v24, v44, v45
	v_cvt_pk_bf16_f32 v25, v46, v47
	v_lshl_add_u64 v[16:17], v[20:21], 1, v[16:17]
	global_store_dwordx4 v[16:17], v[22:25], off nt
	s_and_saveexec_b64 s[84:85], s[14:15]
	s_cbranch_execz .LBB0_512
	global_store_dwordx4 v[18:19], v[40:43], off offset:128 nt
	global_store_dwordx4 v[18:19], v[44:47], off offset:144 nt

; __host__ __device__ __forceinline__ size_t ux_off(int m, int ch) { return ((size_t)((ch >> 4) * UXROWS + (m >> 4)) * UXR + (m & 15)) * 16 + (ch & 15); }
; __device__ __forceinline__ unsigned pk2(float lo, float hi) { typedef __bf16 bf16x2_t_ __attribute__((ext_vector_type(2))); f32x2 v = {lo, hi}; return __builtin_bit_cast(unsigned, __builtin_convertvector(v, bf16x2_t_)); }
;     __device__ __forceinline__ void operator()(const f32x4 (&acc)[2][2][4][2], const pg8::Unit& u, int wr, int wc, int fr, int fq) const {
;     ...
;                 for (int bj = 0; bj < 2; ++bj) {
;                     u32x4 w; w.x = pk2(v[bj][0], v[bj][1]); w.y = pk2(v[bj][2], v[bj][3]); w.z = pk2(v[bj][4], v[bj][5]); w.w = pk2(v[bj][6], v[bj][7]);
;                     *(u32x4*)(bdst + (type == 0 ? ux_off(row, cb0 + bj * 32) : (size_t)(cb0 + bj * 32))) = w;
;                     if (fdst) { *(f32x4*)(fdst + cb0 + bj * 32) = (f32x4){v[bj][0], v[bj][1], v[bj][2], v[bj][3]}; *(f32x4*)(fdst + cb0 + bj * 32 + 4) = (f32x4){v[bj][4], v[bj][5], v[bj][6], v[bj][7]}; }
;                 }
.LBB0_537:
	v_mov_b32_e32 v191, v153
	v_cmp_ne_u64_e64 s[4:5], 0, v[4:5]
	v_lshl_add_u64 v[2:3], v[4:5], 0, v[190:191]
	v_cvt_pk_bf16_f32 v8, v16, v17
	v_cvt_pk_bf16_f32 v9, v18, v19
	v_cvt_pk_bf16_f32 v10, v20, v21
	v_cvt_pk_bf16_f32 v11, v22, v23
	v_lshl_add_u64 v[4:5], v[6:7], 1, v[0:1]
	global_store_dwordx4 v[4:5], v[8:11], off nt
	s_and_saveexec_b64 s[0:1], s[4:5]
	s_cbranch_execz .LBB0_546
	global_store_dwordx4 v[2:3], v[16:19], off nt
	global_store_dwordx4 v[2:3], v[20:23], off offset:16 nt
	s_or_b64 exec, exec, s[0:1]
	s_and_b64 vcc, exec, s[8:9]
	s_mov_b64 s[0:1], -1
	s_cbranch_vccz .LBB0_547

; __host__ __device__ __forceinline__ size_t ux_off(int m, int ch) { return ((size_t)((ch >> 4) * UXROWS + (m >> 4)) * UXR + (m & 15)) * 16 + (ch & 15); }
; __device__ __forceinline__ unsigned pk2(float lo, float hi) { typedef __bf16 bf16x2_t_ __attribute__((ext_vector_type(2))); f32x2 v = {lo, hi}; return __builtin_bit_cast(unsigned, __builtin_convertvector(v, bf16x2_t_)); }
;     __device__ __forceinline__ void operator()(const f32x4 (&acc)[2][2][4][2], const pg8::Unit& u, int wr, int wc, int fr, int fq) const {
;     ...
;                 for (int bj = 0; bj < 2; ++bj) {
;                     u32x4 w; w.x = pk2(v[bj][0], v[bj][1]); w.y = pk2(v[bj][2], v[bj][3]); w.z = pk2(v[bj][4], v[bj][5]); w.w = pk2(v[bj][6], v[bj][7]);
;                     *(u32x4*)(bdst + (type == 0 ? ux_off(row, cb0 + bj * 32) : (size_t)(cb0 + bj * 32))) = w;
;                     if (fdst) { *(f32x4*)(fdst + cb0 + bj * 32) = (f32x4){v[bj][0], v[bj][1], v[bj][2], v[bj][3]}; *(f32x4*)(fdst + cb0 + bj * 32 + 4) = (f32x4){v[bj][4], v[bj][5], v[bj][6], v[bj][7]}; }
;                 }
.LBB0_541:
	v_cvt_pk_bf16_f32 v4, v24, v25
	v_cvt_pk_bf16_f32 v5, v26, v27
	v_cvt_pk_bf16_f32 v6, v28, v29
	v_cvt_pk_bf16_f32 v7, v30, v31
	v_lshl_add_u64 v[0:1], v[128:129], 1, v[0:1]
	global_store_dwordx4 v[0:1], v[4:7], off nt
	s_and_saveexec_b64 s[0:1], s[4:5]
	s_cbranch_execz .LBB0_543
	global_store_dwordx4 v[2:3], v[24:27], off offset:128 nt
	global_store_dwordx4 v[2:3], v[28:31], off offset:144 nt
